# scan step head restructured: record DMAs issued first after the step barrier, then state moves, U loads, previous step's row stores (batched LDS reads)
# baseline (speedup 1.0000x reference)
; #define LAS __attribute__((address_space(3)))
; #define VM_WAIT() asm volatile("s_waitcnt vmcnt(0)" ::: "memory")
; #define GD_GLDS(cidx, buf) do { const unsigned char* src_ = REC + (size_t)(cidx) * GD_REC + lane * 16; \
;         _Pragma("unroll") for (int k_ = 0; k_ < 7; ++k_) __builtin_amdgcn_global_load_lds((const unsigned*)(src_ + (n + 8 * k_) * 1024), (LAS unsigned*)(lds + (buf) * GD_REC + (n + 8 * k_) * 1024), 16, 0, 0); } while (0)
; __device__ __forceinline__ void gdn_scan_phase(const Frame& F0, const Args& a0, int nblk, bool last) {
;     const Frame F = relaunder(F0); const Args a = relaunder_args(a0);
;     const int chain = F.bx; if (chain >= nblk) return;
;     const int d = chain & 1, h = (chain >> 1) & 7, b = chain >> 4;
;     const unsigned char* REC = a.ws + WS_GREC + (size_t)chain * 36 * GD_REC; const float* UB = (const float*)(a.ws + WS_GU) + (size_t)chain * 36 * 8192; const float* GLB = (const float*)(a.ws + WS_GL) + (size_t)chain * 36;
;     bf16* GOb = (bf16*)(a.ws + WS_GO2) + (size_t)d * M * 1024;
;     LAS unsigned char* lds = F.lds + RING_OFF;
;     LAS unsigned char* ost = lds + 2 * GD_REC;
;     const int lane = F.lane, n = F.wave, cc = lane & 15, g = lane >> 4;
;     f32x4 S[8];
; #pragma unroll
;     for (int t = 0; t < 8; ++t) S[t] = (f32x4){0.f, 0.f, 0.f, 0.f};
;     ...
;     f32x4 un[4]; float gln;
;     { const int c0 = GD_CHUNK(0); GD_GLDS(c0, 0);
; #pragma unroll
;       for (int mt = 0; mt < 4; ++mt) un[mt] = *(const f32x4*)(UB + (size_t)c0 * 8192 + ((mt * 8 + n) * 64 + lane) * 4);
;       gln = GLB[c0]; }
;     VM_WAIT(); __syncthreads();
.LBB0_564:
	s_cmp_eq_u32 s24, 3
	s_cselect_b64 s[76:77], -1, 0
	s_cmp_lg_u32 s24, 3
	s_cselect_b64 s[80:81], -1, 0
	s_cmp_le_i32 s64, s18
	s_cselect_b64 s[2:3], -1, 0
	s_and_b64 s[34:35], s[2:3], s[0:1]
	s_andn2_b64 vcc, exec, s[34:35]
	s_cbranch_vccnz .LBB0_687
	s_mov_b32 s0, s93
	s_mov_b32 s7, s94
	s_mov_b32 s6, s95
	s_mov_b32 s1, s92
	v_readlane_b32 s48, v221, 0
	s_waitcnt vmcnt(0)
	v_mbcnt_lo_u32_b32 v0, -1, 0
	v_mbcnt_hi_u32_b32 v0, -1, v0
	v_readlane_b32 s49, v221, 1
	s_mov_b64 s[0:1], s[48:49]
	v_readlane_b32 s50, v221, 2
	v_readlane_b32 s51, v221, 3
	s_mov_b64 s[0:1], s[50:51]
	v_readlane_b32 s52, v221, 4
	v_readlane_b32 s53, v221, 5
	s_mov_b64 s[0:1], s[52:53]
	v_readlane_b32 s54, v221, 6
	v_readlane_b32 s55, v221, 7
	s_mov_b64 s[0:1], s[54:55]
	v_readlane_b32 s56, v221, 8
	v_readlane_b32 s57, v221, 9
	s_mov_b64 s[0:1], s[56:57]
	v_readlane_b32 s58, v221, 10
	v_readlane_b32 s59, v221, 11
	s_mov_b64 s[0:1], s[58:59]
	v_readlane_b32 s60, v221, 12
	v_readlane_b32 s61, v221, 13
	s_mov_b64 s[0:1], s[60:61]
	v_readlane_b32 s62, v221, 14
	v_readlane_b32 s63, v221, 15
	s_mov_b64 s[0:1], s[62:63]
	v_readlane_b32 s48, v221, 16
	v_readlane_b32 s49, v221, 17
	s_mov_b64 s[0:1], s[48:49]
	v_readlane_b32 s50, v221, 18
	v_readlane_b32 s51, v221, 19
	s_mov_b64 s[0:1], s[50:51]
	v_readlane_b32 s52, v221, 20
	v_readlane_b32 s53, v221, 21
	s_mov_b64 s[0:1], s[52:53]
	v_readlane_b32 s54, v221, 22
	v_readlane_b32 s55, v221, 23
	s_mov_b64 s[0:1], s[54:55]
	v_readlane_b32 s56, v221, 24
	v_readlane_b32 s57, v221, 25
	s_mov_b64 s[0:1], s[56:57]
	v_readlane_b32 s58, v221, 26
	v_readlane_b32 s59, v221, 27
	s_mov_b64 s[0:1], s[58:59]
	v_readlane_b32 s60, v221, 28
	v_readlane_b32 s61, v221, 29
	s_mov_b64 s[0:1], s[60:61]
	v_readlane_b32 s62, v221, 30
	v_readlane_b32 s63, v221, 31
	s_mov_b64 s[0:1], s[62:63]
	s_mov_b64 s[0:1], s[40:41]
	s_mov_b64 s[0:1], s[42:43]
	s_mov_b64 s[0:1], s[44:45]
	s_mov_b64 s[0:1], s[46:47]
	s_cmp_gt_i32 s7, 63
	s_cbranch_scc1 .LBB0_578
	s_and_b64 s[2:3], s[76:77], exec
	s_cselect_b32 s22, 4, 0
	s_and_b32 s10, s7, 1
	s_bfe_i32 s11, s7, 0x10000
	s_lshr_b32 s18, s7, 4
	s_mul_i32 s5, s7, 0x120000
	s_mul_hi_i32 s4, s7, 0x120000
	s_add_u32 s5, s0, s5
	s_addc_u32 s4, s1, s4
	s_add_u32 s23, s5, 0x46e00000
	s_addc_u32 s24, s4, 0
	s_mul_i32 s8, s10, 0x1200000
	s_add_u32 s8, s0, s8
	s_mul_i32 s3, s7, 0x1f8000
	s_addc_u32 s9, s1, 0
	s_mul_hi_i32 s2, s7, 0x1f8000
	s_add_u32 s3, s0, s3
	s_addc_u32 s12, s1, s2
	s_add_u32 s2, s3, 0.5
	s_mul_i32 s5, s7, 0x90
	s_addc_u32 s3, s12, 0
	s_mul_hi_i32 s4, s7, 0x90
	s_add_u32 s0, s0, s5
	s_addc_u32 s1, s1, s4
	s_add_u32 s0, s0, 0x4b600000
	s_addc_u32 s1, s1, 0
	s_cmp_eq_u32 s10, 0
	s_cselect_b64 s[4:5], -1, 0
	s_cmp_eq_u32 s10, 1
	v_and_b32_e32 v8, 1, v0
	s_cselect_b64 s[12:13], -1, 0
	s_and_b32 s14, s11, 3
	v_ashrrev_i32_e32 v2, 2, v0
	v_lshlrev_b32_e32 v3, 1, v8
	s_mul_i32 s10, s14, 0xe000
	v_and_or_b32 v9, v2, -4, v3
	s_add_u32 s10, s2, s10
	v_lshlrev_b32_e32 v2, 4, v0
	s_addc_u32 s11, s3, 0
	v_ashrrev_i32_e32 v3, 31, v2
	s_lshl_b32 s30, s6, 10
	v_lshl_add_u64 v[4:5], s[10:11], 0, v[2:3]
	s_ashr_i32 s31, s30, 31
	s_add_i32 s25, s30, 0
	s_add_i32 s68, s30, 0x2000
	v_lshl_add_u64 v[6:7], v[4:5], 0, s[30:31]
	s_mov_b32 m0, s25
	s_ashr_i32 s69, s68, 31
	s_add_i32 s70, s30, 0x4000
	global_load_lds_dwordx4 v[6:7], off nt
	v_lshl_add_u64 v[6:7], v[4:5], 0, s[68:69]
	s_add_i32 m0, s25, 0x2000
	s_ashr_i32 s71, s70, 31
	s_add_i32 s74, s30, 0x6000
	global_load_lds_dwordx4 v[6:7], off nt
	v_lshl_add_u64 v[6:7], v[4:5], 0, s[70:71]
	s_add_i32 m0, s25, 0x4000
	s_ashr_i32 s75, s74, 31
	s_add_i32 s78, s30, 0x8000
	global_load_lds_dwordx4 v[6:7], off nt
	v_lshl_add_u64 v[6:7], v[4:5], 0, s[74:75]
	s_add_i32 m0, s25, 0x6000
	s_ashr_i32 s79, s78, 31
	s_add_i32 s82, s30, 0xa000
	global_load_lds_dwordx4 v[6:7], off nt
	v_lshl_add_u64 v[6:7], v[4:5], 0, s[78:79]
	s_add_i32 m0, s25, 0x8000
	s_ashr_i32 s83, s82, 31
	v_lshl_add_u32 v1, s6, 6, v0
	global_load_lds_dwordx4 v[6:7], off nt
	v_lshl_add_u64 v[6:7], v[4:5], 0, s[82:83]
	s_add_i32 m0, s25, 0xa000
	s_add_i32 s88, s30, 0xc000
	global_load_lds_dwordx4 v[6:7], off nt
	s_ashr_i32 s89, s88, 31
	s_add_i32 m0, s25, 0xc000
	s_lshl_b32 s10, s14, 15
	v_lshlrev_b32_e32 v70, 2, v1
	s_add_u32 s10, s23, s10
	v_add_u32_e32 v72, 0x800, v70
	v_lshl_add_u64 v[4:5], v[4:5], 0, s[88:89]
	s_addc_u32 s11, s24, 0
	v_ashrrev_i32_e32 v71, 31, v70
	v_ashrrev_i32_e32 v73, 31, v72
	v_add_u32_e32 v74, 0x1000, v70
	v_add_u32_e32 v76, 0x1800, v70
	global_load_lds_dwordx4 v[4:5], off nt
	v_lshl_add_u64 v[4:5], v[70:71], 2, s[10:11]
	v_lshl_add_u64 v[6:7], v[72:73], 2, s[10:11]
	v_ashrrev_i32_e32 v75, 31, v74
	v_ashrrev_i32_e32 v77, 31, v76
	global_load_dwordx4 v[60:63], v[4:5], off nt
	global_load_dwordx4 v[56:59], v[6:7], off nt
	v_lshl_add_u64 v[4:5], v[74:75], 2, s[10:11]
	v_lshl_add_u64 v[6:7], v[76:77], 2, s[10:11]
	s_lshl_b32 s10, s14, 2
	global_load_dwordx4 v[52:55], v[4:5], off nt
	global_load_dwordx4 v[48:51], v[6:7], off nt
	v_mov_b32_e32 v4, s10
	global_load_dword v80, v4, s[0:1]
	v_lshl_add_u64 v[78:79], s[2:3], 0, v[2:3]
	v_and_b32_e32 v160, 0xf0, v2
	s_movk_i32 s2, 0xc0
	v_bitop3_b32 v67, v1, v160, s2 bitop3:0x6c
	s_add_i32 s2, 0, 0x1c000
	v_add_u32_e32 v102, s2, v67
	s_lshl_b32 s2, s7, 7
	s_and_b32 s2, s2, 0x700
	s_add_u32 s2, s8, s2
	s_addc_u32 s3, s9, 0
	v_add_u32_e32 v101, 0, v2
	v_lshl_add_u64 v[2:3], s[2:3], 0, v[160:161]
	s_mov_b64 s[2:3], 0x4b800000
	v_lshl_add_u64 v[64:65], v[2:3], 0, s[2:3]
	v_bfe_u32 v2, v0, 3, 1
	v_lshlrev_b32_e32 v0, 1, v0
	v_sub_u32_e32 v10, 63, v9
	v_and_b32_e32 v84, 12, v0
	v_add_u32_e32 v0, 0x200, v1
	v_lshl_or_b32 v2, s6, 1, v2
	v_ashrrev_i32_e32 v69, 4, v0
; #define GD_GLDS(cidx, buf) do { const unsigned char* src_ = REC + (size_t)(cidx) * GD_REC + lane * 16; \
;         _Pragma("unroll") for (int k_ = 0; k_ < 7; ++k_) __builtin_amdgcn_global_load_lds((const unsigned*)(src_ + (n + 8 * k_) * 1024), (LAS unsigned*)(lds + (buf) * GD_REC + (n + 8 * k_) * 1024), 16, 0, 0); } while (0)
; #define GD_STORE_ROWS(cidx, buf) do { _Pragma("unroll") for (int i_ = 0; i_ < 2; ++i_) { const int id_ = F.tid + 512 * i_, row_ = id_ >> 4, ch_ = id_ & 15; \
;         const v4u v_ = *(const LAS v4u*)(ost + (buf) * 16384 + row_ * 256 + ((ch_ ^ (((row_ >> 2) & 3) << 2)) * 16)); \
;         *(v4u*)(GOb + (size_t)(b * TT + 64 * (cidx) + row_) * 1024 + h * 128 + ch_ * 8) = v_; } } while (0)
; __device__ __forceinline__ void gdn_scan_phase(const Frame& F0, const Args& a0, int nblk, bool last) {
;     ...
;     for (int s = 0; s < 36; ++s) {
;         const int c = GD_CHUNK(s);
;         f32x4 V[4]; const float gl = gln;
; #pragma unroll
;         for (int mt = 0; mt < 4; ++mt) V[mt] = un[mt];
;         if (cprev >= 0 && !(last && cprev < 4)) GD_STORE_ROWS(cprev, (s + 1) & 1);
;         if (s + 1 < 36) { const int cn = GD_CHUNK(s + 1);
; #pragma unroll
;             for (int mt = 0; mt < 4; ++mt) un[mt] = *(const f32x4*)(UB + (size_t)cn * 8192 + ((mt * 8 + n) * 64 + lane) * 4);
;             gln = GLB[cn];
;             GD_GLDS(cn, (s + 1) & 1); }
	v_cndmask_b32_e64 v0, v10, v9, s[4:5]
	v_lshlrev_b32_e32 v97, 8, v0
	v_bitop3_b32 v0, v0, v2, 12 bitop3:0x6c
	v_lshlrev_b32_e32 v98, 4, v0
	v_or_b32_e32 v0, 1, v9
	v_ashrrev_i32_e32 v82, 4, v1
	v_sub_u32_e32 v1, 63, v0
	v_cndmask_b32_e64 v0, v1, v0, s[4:5]
	v_lshlrev_b32_e32 v99, 8, v0
	v_bitop3_b32 v0, v0, v2, 12 bitop3:0x6c
	v_lshlrev_b32_e32 v100, 4, v0
	v_add_u32_e32 v0, 16, v9
	v_sub_u32_e32 v1, 47, v9
	v_cndmask_b32_e64 v0, v1, v0, s[4:5]
	v_lshlrev_b32_e32 v93, 8, v0
	v_bitop3_b32 v0, v0, v2, 12 bitop3:0x6c
	v_lshlrev_b32_e32 v94, 4, v0
	v_add_u32_e32 v0, 17, v9
	v_sub_u32_e32 v1, 46, v9
	v_cndmask_b32_e64 v0, v1, v0, s[4:5]
	v_lshlrev_b32_e32 v95, 8, v0
	v_bitop3_b32 v0, v0, v2, 12 bitop3:0x6c
	v_lshlrev_b32_e32 v96, 4, v0
	v_add_u32_e32 v0, 32, v9
	v_sub_u32_e32 v1, 31, v9
	v_cndmask_b32_e64 v0, v1, v0, s[4:5]
	v_lshlrev_b32_e32 v89, 8, v0
	v_bitop3_b32 v0, v0, v2, 12 bitop3:0x6c
	v_lshlrev_b32_e32 v90, 4, v0
	v_add_u32_e32 v0, 33, v9
	v_sub_u32_e32 v1, 30, v9
	v_cndmask_b32_e64 v0, v1, v0, s[4:5]
	v_lshlrev_b32_e32 v91, 8, v0
	v_bitop3_b32 v0, v0, v2, 12 bitop3:0x6c
	v_lshlrev_b32_e32 v92, 4, v0
	v_add_u32_e32 v0, 48, v9
	v_sub_u32_e32 v1, 15, v9
	v_cndmask_b32_e64 v0, v1, v0, s[4:5]
	v_lshlrev_b32_e32 v85, 8, v0
	v_bitop3_b32 v0, v0, v2, 12 bitop3:0x6c
	v_lshlrev_b32_e32 v86, 4, v0
	v_add_u32_e32 v0, 49, v9
	v_sub_u32_e32 v1, 14, v9
	v_cndmask_b32_e64 v0, v1, v0, s[4:5]
	s_waitcnt vmcnt(0)
	v_lshlrev_b32_e32 v87, 8, v0
	v_bitop3_b32 v0, v0, v2, 12 bitop3:0x6c
	v_lshlrev_b32_e32 v88, 4, v0
	v_cmp_eq_u32_e64 s[2:3], 0, v8
	v_mov_b32_e32 v0, 0
	s_mov_b32 s19, 0
	s_mulk_i32 s18, 0x900
	v_lshlrev_b32_e32 v83, 8, v82
	v_lshlrev_b32_e32 v81, 8, v69
	v_cndmask_b32_e64 v68, 0, 2, s[2:3]
	v_cndmask_b32_e64 v66, 1, 3, s[2:3]
	s_mov_b32 s27, -1
	s_mov_b32 s26, 38
	s_mov_b32 s8, 0
	v_mov_b32_e32 v1, v0
	v_mov_b32_e32 v2, v0
	v_mov_b32_e32 v3, v0
	v_mov_b32_e32 v4, v0
	v_mov_b32_e32 v5, v0
	v_mov_b32_e32 v6, v0
	v_mov_b32_e32 v7, v0
	v_mov_b32_e32 v8, v0
	v_mov_b32_e32 v9, v0
	v_mov_b32_e32 v10, v0
	v_mov_b32_e32 v11, v0
	v_mov_b32_e32 v12, v0
	v_mov_b32_e32 v13, v0
	v_mov_b32_e32 v14, v0
	v_mov_b32_e32 v15, v0
	v_mov_b32_e32 v16, v0
	v_mov_b32_e32 v17, v0
	v_mov_b32_e32 v18, v0
	v_mov_b32_e32 v19, v0
	v_mov_b32_e32 v20, v0
	v_mov_b32_e32 v21, v0
	v_mov_b32_e32 v22, v0
	v_mov_b32_e32 v23, v0
	v_mov_b32_e32 v24, v0
	v_mov_b32_e32 v25, v0
	v_mov_b32_e32 v26, v0
	v_mov_b32_e32 v27, v0
	v_mov_b32_e32 v28, v0
	v_mov_b32_e32 v29, v0
	v_mov_b32_e32 v30, v0
	v_mov_b32_e32 v31, v0
	s_waitcnt vmcnt(0) lgkmcnt(0)
	s_barrier
	s_branch .Lscan_head
.LBB0_567:
	s_mov_b32 s8, s29
.Lscan_head:
	s_mov_b32 s66, s27
	s_add_i32 s29, s8, 1
	s_andn2_b64 vcc, exec, s[12:13]
	s_mov_b32 s6, s29
	s_cbranch_vccnz .Lscan_cn
	s_cmp_gt_u32 s8, 2
	s_mov_b32 s6, s26
	s_cbranch_scc1 .Lscan_cn
	s_sub_i32 s6, 2, s8
.Lscan_cn:
	s_cmp_gt_u32 s8, 3
	s_cselect_b32 s7, 39, 3
	s_add_i32 s7, s7, s26
	s_sub_i32 s7, s7, 38
	s_and_b64 s[10:11], s[4:5], exec
	s_cselect_b32 s27, s8, s7
	v_mad_i64_i32 v[104:105], s[98:99], s6, v193, v[78:79]
	s_bitcmp1_b32 s29, 0
	s_cselect_b32 s67, 0xe000, 0
	s_add_i32 s67, s25, s67
	v_lshl_add_u64 v[106:107], v[104:105], 0, s[30:31]
	s_mov_b32 m0, s67
	s_nop 0
	global_load_lds_dwordx4 v[106:107], off nt
	v_lshl_add_u64 v[106:107], v[104:105], 0, s[68:69]
	s_add_i32 m0, s67, 0x2000
	s_nop 0
	global_load_lds_dwordx4 v[106:107], off nt
	v_lshl_add_u64 v[106:107], v[104:105], 0, s[70:71]
	s_add_i32 m0, s67, 0x4000
	s_nop 0
	global_load_lds_dwordx4 v[106:107], off nt
	v_lshl_add_u64 v[106:107], v[104:105], 0, s[74:75]
	s_add_i32 m0, s67, 0x6000
	s_nop 0
	global_load_lds_dwordx4 v[106:107], off nt
	v_lshl_add_u64 v[106:107], v[104:105], 0, s[78:79]
	s_add_i32 m0, s67, 0x8000
	s_nop 0
	global_load_lds_dwordx4 v[106:107], off nt
	v_lshl_add_u64 v[106:107], v[104:105], 0, s[82:83]
	s_add_i32 m0, s67, 0xa000
	v_lshl_add_u64 v[104:105], v[104:105], 0, s[88:89]
	global_load_lds_dwordx4 v[106:107], off nt
	s_add_i32 m0, s67, 0xc000
	s_nop 0
	global_load_lds_dwordx4 v[104:105], off nt
	s_cmp_eq_u32 s66, -1
	s_cbranch_scc1 .Lscan_ld
	v_mov_b64_e32 v[50:51], v[34:35]
	v_mov_b64_e32 v[54:55], v[38:39]
	v_mov_b64_e32 v[58:59], v[42:43]
	v_mov_b64_e32 v[62:63], v[46:47]
	v_mov_b64_e32 v[48:49], v[32:33]
	v_mov_b64_e32 v[52:53], v[36:37]
	v_mov_b64_e32 v[56:57], v[40:41]
	v_mov_b64_e32 v[60:61], v[44:45]
	v_mov_b32_e32 v80, v103
.Lscan_ld:
	s_ashr_i32 s7, s6, 31
	s_lshl_b64 s[10:11], s[6:7], 15
	s_add_u32 s10, s23, s10
	s_addc_u32 s11, s24, s11
	v_lshl_add_u64 v[32:33], v[70:71], 2, s[10:11]
	v_lshl_add_u64 v[34:35], v[72:73], 2, s[10:11]
	global_load_dwordx4 v[44:47], v[32:33], off nt
	global_load_dwordx4 v[40:43], v[34:35], off nt
	v_lshl_add_u64 v[32:33], v[74:75], 2, s[10:11]
	v_lshl_add_u64 v[34:35], v[76:77], 2, s[10:11]
	s_lshl_b64 s[10:11], s[6:7], 2
	s_add_u32 s10, s0, s10
	s_addc_u32 s11, s1, s11
	global_load_dwordx4 v[36:39], v[32:33], off nt
	s_nop 0
	global_load_dwordx4 v[32:35], v[34:35], off nt
	global_load_dword v103, v161, s[10:11]
	s_cmp_lt_i32 s66, s22
	s_cbranch_scc1 .Lscan_go
	s_andn2_b32 s67, 0x4000, s19
	v_add_u32_e32 v214, s67, v102
	s_lshl_b32 s67, s66, 6
	v_add_u32_e32 v208, v214, v83
	s_add_i32 s67, s67, s18
	ds_read_b128 v[208:211], v208
	v_add_u32_e32 v216, v214, v81
	ds_read_b128 v[216:219], v216
	v_add_u32_e32 v212, s67, v82
	v_ashrrev_i32_e32 v213, 31, v212
	v_lshlrev_b64 v[212:213], 11, v[212:213]
	v_lshl_add_u64 v[212:213], v[64:65], 0, v[212:213]
	v_add_u32_e32 v214, s67, v69
	v_ashrrev_i32_e32 v215, 31, v214
	v_lshlrev_b64 v[214:215], 11, v[214:215]
	v_lshl_add_u64 v[214:215], v[64:65], 0, v[214:215]
	s_waitcnt lgkmcnt(1)
	global_store_dwordx4 v[212:213], v[208:211], off
	s_waitcnt lgkmcnt(0)
	global_store_dwordx4 v[214:215], v[216:219], off
; #define LAS __attribute__((address_space(3)))
; #define GD_LOAD8(dst, f0) do { _Pragma("unroll") for (int i_ = 0; i_ < 8; ++i_) dst[i_] = GD_FRAG((f0) + i_); } while (0)
; #define GD_PIN() __builtin_amdgcn_sched_barrier(0)
; __device__ __forceinline__ void gdn_scan_phase(const Frame& F0, const Args& a0, int nblk, bool last) {
;     ...
;         const LAS unsigned char* Bf = lds + (s & 1) * GD_REC + lane * 16;
;     ...
;         bf16x8 fA[8], fB[8], fC[8];
;     ...
;         GD_LOAD8(fA, 0); GD_LOAD8(fB, 8);
;         bf16x8 Sf[4];
; #pragma unroll
;         for (int kb = 0; kb < 4; ++kb) Sf[kb] = pack8(S[2 * kb], S[2 * kb + 1]);
;         f32x4 O[4];
; #pragma unroll
;         for (int mt = 0; mt < 4; ++mt) O[mt] = (f32x4){0.f, 0.f, 0.f, 0.f};
;         GD_PIN();
; #pragma unroll
;         for (int i = 0; i < 8; ++i) V[i >> 2] = __builtin_amdgcn_mfma_f32_16x16x32_bf16(fA[i], Sf[i & 3], V[i >> 2], 0, 0, 0);
;         GD_PIN(); GD_LOAD8(fC, 16); GD_PIN();
; #pragma unroll
;         for (int i = 0; i < 8; ++i) V[2 + (i >> 2)] = __builtin_amdgcn_mfma_f32_16x16x32_bf16(fB[i], Sf[i & 3], V[2 + (i >> 2)], 0, 0, 0);
;         GD_PIN(); GD_LOAD8(fA, 24); GD_PIN();
; #pragma unroll
;         for (int i = 0; i < 8; ++i) O[i >> 2] = __builtin_amdgcn_mfma_f32_16x16x32_bf16(fC[i], Sf[i & 3], O[i >> 2], 0, 0, 0);
;         GD_PIN(); GD_LOAD8(fB, 32); GD_PIN();
; #pragma unroll
;         for (int i = 0; i < 8; ++i) O[2 + (i >> 2)] = __builtin_amdgcn_mfma_f32_16x16x32_bf16(fA[i], Sf[i & 3], O[2 + (i >> 2)], 0, 0, 0);
;         GD_PIN(); GD_LOAD8(fC, 40); GD_PIN();
;         bf16x8 Vf[2]; Vf[0] = pack8(V[0], V[1]); Vf[1] = pack8(V[2], V[3]);
; #pragma unroll
;         for (int t = 0; t < 8; ++t) S[t] = S[t] * gl;
; #pragma unroll
;         for (int i = 0; i < 8; ++i) S[i >> 1] = __builtin_amdgcn_mfma_f32_16x16x32_bf16(fB[i], Vf[i & 1], S[i >> 1], 0, 0, 0);
.Lscan_go:
	v_cvt_pk_bf16_f32 v170, v28, v29
	v_cvt_pk_bf16_f32 v171, v30, v31
	v_cvt_pk_bf16_f32 v172, v24, v25
	v_cvt_pk_bf16_f32 v173, v26, v27
	v_cvt_pk_bf16_f32 v174, v20, v21
	s_and_b32 s6, s8, 1
	s_mul_i32 s7, s6, 0xe000
	v_add_u32_e32 v160, s7, v101
	ds_read_b128 v[104:107], v160
	ds_read_b128 v[108:111], v160 offset:1024
	ds_read_b128 v[112:115], v160 offset:2048
	ds_read_b128 v[116:119], v160 offset:3072
	ds_read_b128 v[120:123], v160 offset:4096
	ds_read_b128 v[124:127], v160 offset:5120
	ds_read_b128 v[128:131], v160 offset:6144
	ds_read_b128 v[132:135], v160 offset:7168
	ds_read_b128 v[136:139], v160 offset:8192
	ds_read_b128 v[140:143], v160 offset:9216
	ds_read_b128 v[144:147], v160 offset:10240
	ds_read_b128 v[148:151], v160 offset:11264
	ds_read_b128 v[152:155], v160 offset:12288
	ds_read_b128 v[156:159], v160 offset:13312
	ds_read_b128 v[162:165], v160 offset:14336
	ds_read_b128 v[166:169], v160 offset:15360
	v_cvt_pk_bf16_f32 v175, v22, v23
	v_cvt_pk_bf16_f32 v176, v16, v17
	v_cvt_pk_bf16_f32 v177, v18, v19
	v_cvt_pk_bf16_f32 v178, v12, v13
	v_cvt_pk_bf16_f32 v179, v14, v15
	v_cvt_pk_bf16_f32 v180, v8, v9
	v_cvt_pk_bf16_f32 v181, v10, v11
	v_cvt_pk_bf16_f32 v196, v4, v5
	v_cvt_pk_bf16_f32 v197, v6, v7
	v_cvt_pk_bf16_f32 v198, v0, v1
	v_cvt_pk_bf16_f32 v199, v2, v3
	s_waitcnt lgkmcnt(0)
	v_mfma_f32_16x16x32_bf16 v[60:63], v[104:107], v[170:173], v[60:63]
	v_mfma_f32_16x16x32_bf16 v[56:59], v[120:123], v[170:173], v[56:59]
	v_mfma_f32_16x16x32_bf16 v[60:63], v[108:111], v[174:177], v[60:63]
	v_mfma_f32_16x16x32_bf16 v[56:59], v[124:127], v[174:177], v[56:59]
	v_mfma_f32_16x16x32_bf16 v[60:63], v[112:115], v[178:181], v[60:63]
	v_mfma_f32_16x16x32_bf16 v[56:59], v[128:131], v[178:181], v[56:59]
	v_mfma_f32_16x16x32_bf16 v[60:63], v[116:119], v[196:199], v[60:63]
	v_mfma_f32_16x16x32_bf16 v[56:59], v[132:135], v[196:199], v[56:59]
	ds_read_b128 v[104:107], v160 offset:16384
	ds_read_b128 v[108:111], v160 offset:17408
	ds_read_b128 v[112:115], v160 offset:18432
	ds_read_b128 v[116:119], v160 offset:19456
	ds_read_b128 v[120:123], v160 offset:20480
	ds_read_b128 v[124:127], v160 offset:21504
	ds_read_b128 v[128:131], v160 offset:22528
	ds_read_b128 v[132:135], v160 offset:23552
	v_mfma_f32_16x16x32_bf16 v[52:55], v[136:139], v[170:173], v[52:55]
	v_mfma_f32_16x16x32_bf16 v[48:51], v[152:155], v[170:173], v[48:51]
	v_mfma_f32_16x16x32_bf16 v[52:55], v[140:143], v[174:177], v[52:55]
	v_mfma_f32_16x16x32_bf16 v[48:51], v[156:159], v[174:177], v[48:51]
	v_mfma_f32_16x16x32_bf16 v[52:55], v[144:147], v[178:181], v[52:55]
	v_mfma_f32_16x16x32_bf16 v[48:51], v[162:165], v[178:181], v[48:51]
	v_mfma_f32_16x16x32_bf16 v[52:55], v[148:151], v[196:199], v[52:55]
	v_mfma_f32_16x16x32_bf16 v[48:51], v[166:169], v[196:199], v[48:51]
	ds_read_b128 v[136:139], v160 offset:24576
	ds_read_b128 v[140:143], v160 offset:25600
	ds_read_b128 v[144:147], v160 offset:26624
	ds_read_b128 v[148:151], v160 offset:27648
	ds_read_b128 v[152:155], v160 offset:28672
	ds_read_b128 v[156:159], v160 offset:29696
	ds_read_b128 v[162:165], v160 offset:30720
	ds_read_b128 v[166:169], v160 offset:31744
	s_waitcnt lgkmcnt(0)
	v_mfma_f32_16x16x32_bf16 v[104:107], v[104:107], v[170:173], 0
	v_mfma_f32_16x16x32_bf16 v[104:107], v[108:111], v[174:177], v[104:107]
	v_mfma_f32_16x16x32_bf16 v[108:111], v[120:123], v[170:173], 0
	v_mfma_f32_16x16x32_bf16 v[108:111], v[124:127], v[174:177], v[108:111]
	v_mfma_f32_16x16x32_bf16 v[104:107], v[112:115], v[178:181], v[104:107]
	v_mfma_f32_16x16x32_bf16 v[108:111], v[128:131], v[178:181], v[108:111]
	v_mfma_f32_16x16x32_bf16 v[104:107], v[116:119], v[196:199], v[104:107]
	v_mfma_f32_16x16x32_bf16 v[108:111], v[132:135], v[196:199], v[108:111]
	ds_read_b128 v[112:115], v160 offset:32768
	ds_read_b128 v[116:119], v160 offset:33792
	ds_read_b128 v[120:123], v160 offset:34816
	ds_read_b128 v[124:127], v160 offset:35840
	ds_read_b128 v[128:131], v160 offset:36864
	ds_read_b128 v[132:135], v160 offset:37888
	ds_read_b128 v[200:203], v160 offset:38912
	ds_read_b128 v[204:207], v160 offset:39936
	v_mfma_f32_16x16x32_bf16 v[136:139], v[136:139], v[170:173], 0
	v_mfma_f32_16x16x32_bf16 v[136:139], v[140:143], v[174:177], v[136:139]
	v_mfma_f32_16x16x32_bf16 v[140:143], v[152:155], v[170:173], 0
	v_mfma_f32_16x16x32_bf16 v[140:143], v[156:159], v[174:177], v[140:143]
	v_mfma_f32_16x16x32_bf16 v[136:139], v[144:147], v[178:181], v[136:139]
	v_mfma_f32_16x16x32_bf16 v[140:143], v[162:165], v[178:181], v[140:143]
	v_mfma_f32_16x16x32_bf16 v[136:139], v[148:151], v[196:199], v[136:139]
	v_mfma_f32_16x16x32_bf16 v[140:143], v[166:169], v[196:199], v[140:143]
	ds_read_b128 v[144:147], v160 offset:40960
	ds_read_b128 v[148:151], v160 offset:41984
	ds_read_b128 v[152:155], v160 offset:43008
	ds_read_b128 v[156:159], v160 offset:44032
	ds_read_b128 v[162:165], v160 offset:45056
	ds_read_b128 v[166:169], v160 offset:46080
	ds_read_b128 v[170:173], v160 offset:47104
	ds_read_b128 v[174:177], v160 offset:48128
	v_cvt_pk_bf16_f32 v178, v60, v61
	v_cvt_pk_bf16_f32 v179, v62, v63
	v_cvt_pk_bf16_f32 v180, v56, v57
	v_cvt_pk_bf16_f32 v181, v58, v59
	v_pk_mul_f32 v[30:31], v[30:31], v[80:81] op_sel_hi:[1,0]
	v_pk_mul_f32 v[28:29], v[28:29], v[80:81] op_sel_hi:[1,0]
	v_pk_mul_f32 v[26:27], v[26:27], v[80:81] op_sel_hi:[1,0]
	v_pk_mul_f32 v[24:25], v[24:25], v[80:81] op_sel_hi:[1,0]
	v_pk_mul_f32 v[22:23], v[22:23], v[80:81] op_sel_hi:[1,0]
	v_pk_mul_f32 v[20:21], v[20:21], v[80:81] op_sel_hi:[1,0]
	v_pk_mul_f32 v[18:19], v[18:19], v[80:81] op_sel_hi:[1,0]
	v_pk_mul_f32 v[16:17], v[16:17], v[80:81] op_sel_hi:[1,0]
	s_waitcnt lgkmcnt(0)
; #define LAS __attribute__((address_space(3)))
; __device__ __forceinline__ unsigned pk2(float lo, float hi) { return __builtin_bit_cast(unsigned, __builtin_convertvector((f32x2p){lo, hi}, bf16x2p)); }
; #define GD_PIN() __builtin_amdgcn_sched_barrier(0)
; __device__ __forceinline__ void gdn_scan_phase(const Frame& F0, const Args& a0, int nblk, bool last) {
;     ...
;         for (int i = 0; i < 8; ++i) S[i >> 1] = __builtin_amdgcn_mfma_f32_16x16x32_bf16(fB[i], Vf[i & 1], S[i >> 1], 0, 0, 0);
;         GD_PIN();
; #pragma unroll
;         for (int i_ = 0; i_ < 8; ++i_) if (i_ != 1 && i_ != 3) fA[i_] = GD_FRAG(48 + i_);
;         GD_PIN();
; #pragma unroll
;         for (int i = 0; i < 8; ++i) S[4 + (i >> 1)] = __builtin_amdgcn_mfma_f32_16x16x32_bf16(fC[i], Vf[i & 1], S[4 + (i >> 1)], 0, 0, 0);
; #pragma unroll
;         for (int i = 0; i < 8; ++i) if (i != 1 && i != 3) O[i >> 1] = __builtin_amdgcn_mfma_f32_16x16x32_bf16(fA[i], Vf[i & 1], O[i >> 1], 0, 0, 0);
;     ...
;         if (!(last && c < 4)) {
;             LAS unsigned char* ob = ost + (s & 1) * 16384;
;             const bool ev = !(cc & 1);
; #pragma unroll
;             for (int mt = 0; mt < 4; ++mt) {
;                 const float s0 = ev ? O[mt][2] : O[mt][0], s1 = ev ? O[mt][3] : O[mt][1];
;                 const float r0 = __builtin_bit_cast(float, __builtin_amdgcn_mov_dpp(__builtin_bit_cast(int, s0), 0xB1, 0xF, 0xF, true));
;                 const float r1 = __builtin_bit_cast(float, __builtin_amdgcn_mov_dpp(__builtin_bit_cast(int, s1), 0xB1, 0xF, 0xF, true));
;                 const unsigned w0 = ev ? pk2(O[mt][0], r0) : pk2(r0, O[mt][2]), w1 = ev ? pk2(O[mt][1], r1) : pk2(r1, O[mt][3]);
; #pragma unroll
;                 for (int e = 0; e < 2; ++e) { const int p = 16 * mt + 4 * g + (ev ? 0 : 2) + e, tok = d ? 63 - p : p;
;                     *(LAS unsigned*)(ob + tok * 256 + (((2 * n + (cc >> 3)) ^ (((tok >> 2) & 3) << 2)) * 16) + (cc & 6) * 2) = e ? w1 : w0; } }
;         }
	v_mfma_f32_16x16x32_bf16 v[28:31], v[112:115], v[178:181], v[28:31]
	v_cvt_pk_bf16_f32 v196, v52, v53
	v_cvt_pk_bf16_f32 v197, v54, v55
	v_cvt_pk_bf16_f32 v198, v48, v49
	v_mfma_f32_16x16x32_bf16 v[24:27], v[120:123], v[178:181], v[24:27]
	v_cvt_pk_bf16_f32 v199, v50, v51
	v_pk_mul_f32 v[14:15], v[14:15], v[80:81] op_sel_hi:[1,0]
	v_pk_mul_f32 v[12:13], v[12:13], v[80:81] op_sel_hi:[1,0]
	v_mfma_f32_16x16x32_bf16 v[20:23], v[128:131], v[178:181], v[20:23]
	v_mul_f32_e64 v10, v10, v80
	v_mul_f32_e64 v11, v11, v80
	v_pk_mul_f32 v[8:9], v[8:9], v[80:81] op_sel_hi:[1,0]
	v_pk_mul_f32 v[6:7], v[6:7], v[80:81] op_sel_hi:[1,0]
	v_mfma_f32_16x16x32_bf16 v[16:19], v[200:203], v[178:181], v[16:19]
	v_mul_f32_e64 v4, v4, v80
	v_mul_f32_e64 v5, v5, v80
	v_pk_mul_f32 v[2:3], v[2:3], v[80:81] op_sel_hi:[1,0]
	v_pk_mul_f32 v[0:1], v[0:1], v[80:81] op_sel_hi:[1,0]
	v_mfma_f32_16x16x32_bf16 v[28:31], v[116:119], v[196:199], v[28:31]
	v_mfma_f32_16x16x32_bf16 v[24:27], v[124:127], v[196:199], v[24:27]
	v_mfma_f32_16x16x32_bf16 v[20:23], v[132:135], v[196:199], v[20:23]
	v_mfma_f32_16x16x32_bf16 v[16:19], v[204:207], v[196:199], v[16:19]
	ds_read_b128 v[48:51], v160 offset:49152
	ds_read_b128 v[52:55], v160 offset:51200
	ds_read_b128 v[112:115], v160 offset:53248
	ds_read_b128 v[116:119], v160 offset:54272
	ds_read_b128 v[120:123], v160 offset:55296
	ds_read_b128 v[124:127], v160 offset:56320
	s_waitcnt lgkmcnt(0)
	v_mfma_f32_16x16x32_bf16 v[60:63], v[48:51], v[178:181], v[104:107]
	s_cmp_lt_i32 s27, 4
	s_cselect_b64 s[8:9], -1, 0
	s_and_b64 s[8:9], s[76:77], s[8:9]
	v_mfma_f32_16x16x32_bf16 v[48:51], v[112:115], v[178:181], v[136:139]
	s_and_b64 vcc, exec, s[8:9]
	v_mfma_f32_16x16x32_bf16 v[12:15], v[144:147], v[178:181], v[12:15]
	v_mfma_f32_16x16x32_bf16 v[8:11], v[152:155], v[178:181], v[8:11]
	v_mfma_f32_16x16x32_bf16 v[4:7], v[162:165], v[178:181], v[4:7]
	v_mfma_f32_16x16x32_bf16 v[0:3], v[170:173], v[178:181], v[0:3]
	v_mfma_f32_16x16x32_bf16 v[56:59], v[52:55], v[178:181], v[108:111]
	v_mfma_f32_16x16x32_bf16 v[52:55], v[116:119], v[196:199], v[48:51]
	v_mfma_f32_16x16x32_bf16 v[48:51], v[120:123], v[178:181], v[140:143]
	v_mfma_f32_16x16x32_bf16 v[12:15], v[148:151], v[196:199], v[12:15]
	v_mfma_f32_16x16x32_bf16 v[8:11], v[156:159], v[196:199], v[8:11]
	v_mfma_f32_16x16x32_bf16 v[4:7], v[166:169], v[196:199], v[4:7]
	v_mfma_f32_16x16x32_bf16 v[0:3], v[174:177], v[196:199], v[0:3]
	v_mfma_f32_16x16x32_bf16 v[48:51], v[124:127], v[196:199], v[48:51]
	s_cbranch_vccnz .LBB0_574
	s_lshl_b32 s6, s6, 14
	s_add_i32 s6, s6, 0
	v_cmp_eq_u32_e32 vcc, 1, v68
	s_add_i32 s36, s6, 0x1c000
	v_cmp_eq_u32_e64 s[6:7], 2, v68
	v_cndmask_b32_e32 v80, v60, v61, vcc
	v_cmp_eq_u32_e64 s[8:9], 3, v68
	v_cndmask_b32_e64 v80, v80, v62, s[6:7]
	v_cmp_eq_u32_e64 s[10:11], 1, v66
	v_cndmask_b32_e64 v80, v80, v63, s[8:9]
	v_cmp_eq_u32_e64 s[14:15], 2, v66
	v_cndmask_b32_e64 v104, v60, v61, s[10:11]
	v_mov_b32_dpp v80, v80 quad_perm:[1,0,3,2] row_mask:0xf bank_mask:0xf bound_ctrl:1
	v_cndmask_b32_e64 v104, v104, v62, s[14:15]
	v_cmp_eq_u32_e64 s[16:17], 3, v66
	v_cndmask_b32_e64 v60, v80, v60, s[2:3]
	v_cndmask_b32_e64 v62, v62, v80, s[2:3]
	v_cndmask_b32_e64 v104, v104, v63, s[16:17]
	v_cvt_pk_bf16_f32 v60, v60, v62
	v_add_u32_e32 v62, s36, v97
	v_mov_b32_dpp v104, v104 quad_perm:[1,0,3,2] row_mask:0xf bank_mask:0xf bound_ctrl:1
	v_cndmask_b32_e64 v61, v104, v61, s[2:3]
	v_cndmask_b32_e64 v63, v63, v104, s[2:3]
	v_add3_u32 v62, v62, v98, v84
	ds_write_b32 v62, v60
	v_cvt_pk_bf16_f32 v60, v61, v63
	v_add_u32_e32 v61, s36, v99
	v_add3_u32 v61, v61, v100, v84
	ds_write_b32 v61, v60
	v_cndmask_b32_e32 v60, v56, v57, vcc
	v_cndmask_b32_e64 v60, v60, v58, s[6:7]
	v_cndmask_b32_e64 v60, v60, v59, s[8:9]
	v_cndmask_b32_e64 v61, v56, v57, s[10:11]
	v_cndmask_b32_e64 v61, v61, v58, s[14:15]
	v_mov_b32_dpp v60, v60 quad_perm:[1,0,3,2] row_mask:0xf bank_mask:0xf bound_ctrl:1
	v_cndmask_b32_e64 v61, v61, v59, s[16:17]
	v_cndmask_b32_e64 v56, v60, v56, s[2:3]
	v_cndmask_b32_e64 v58, v58, v60, s[2:3]
	v_mov_b32_dpp v61, v61 quad_perm:[1,0,3,2] row_mask:0xf bank_mask:0xf bound_ctrl:1
	v_cvt_pk_bf16_f32 v56, v56, v58
	v_add_u32_e32 v58, s36, v93
	v_cndmask_b32_e64 v57, v61, v57, s[2:3]
	v_cndmask_b32_e64 v59, v59, v61, s[2:3]
	v_add3_u32 v58, v58, v94, v84
	ds_write_b32 v58, v56
	v_cvt_pk_bf16_f32 v56, v57, v59
	v_add_u32_e32 v57, s36, v95
	v_add3_u32 v57, v57, v96, v84
	ds_write_b32 v57, v56
	v_cndmask_b32_e32 v56, v52, v53, vcc
	v_cndmask_b32_e64 v56, v56, v54, s[6:7]
	v_cndmask_b32_e64 v56, v56, v55, s[8:9]
	v_cndmask_b32_e64 v57, v52, v53, s[10:11]
	v_cndmask_b32_e64 v57, v57, v54, s[14:15]
	v_mov_b32_dpp v56, v56 quad_perm:[1,0,3,2] row_mask:0xf bank_mask:0xf bound_ctrl:1
	v_cndmask_b32_e64 v57, v57, v55, s[16:17]
	v_cndmask_b32_e64 v52, v56, v52, s[2:3]
	v_cndmask_b32_e64 v54, v54, v56, s[2:3]
	v_mov_b32_dpp v57, v57 quad_perm:[1,0,3,2] row_mask:0xf bank_mask:0xf bound_ctrl:1
	v_cvt_pk_bf16_f32 v52, v52, v54
	v_add_u32_e32 v54, s36, v89
	v_cndmask_b32_e64 v53, v57, v53, s[2:3]
	v_cndmask_b32_e64 v55, v55, v57, s[2:3]
	v_add3_u32 v54, v54, v90, v84
	ds_write_b32 v54, v52
	v_cvt_pk_bf16_f32 v52, v53, v55
	v_add_u32_e32 v53, s36, v91
	v_add3_u32 v53, v53, v92, v84
	ds_write_b32 v53, v52
	v_cndmask_b32_e32 v52, v48, v49, vcc
	v_cndmask_b32_e64 v52, v52, v50, s[6:7]
	v_cndmask_b32_e64 v52, v52, v51, s[8:9]
	v_cndmask_b32_e64 v53, v48, v49, s[10:11]
	v_cndmask_b32_e64 v53, v53, v50, s[14:15]
	v_mov_b32_dpp v52, v52 quad_perm:[1,0,3,2] row_mask:0xf bank_mask:0xf bound_ctrl:1
	v_cndmask_b32_e64 v53, v53, v51, s[16:17]
	v_cndmask_b32_e64 v48, v52, v48, s[2:3]
	v_cndmask_b32_e64 v50, v50, v52, s[2:3]
	v_mov_b32_dpp v53, v53 quad_perm:[1,0,3,2] row_mask:0xf bank_mask:0xf bound_ctrl:1
	v_cvt_pk_bf16_f32 v48, v48, v50
	v_add_u32_e32 v50, s36, v85
	v_cndmask_b32_e64 v49, v53, v49, s[2:3]
	v_cndmask_b32_e64 v51, v51, v53, s[2:3]
	v_add3_u32 v50, v50, v86, v84
	ds_write_b32 v50, v48
	v_cvt_pk_bf16_f32 v48, v49, v51
	v_add_u32_e32 v49, s36, v87
	v_add3_u32 v49, v49, v88, v84
	ds_write_b32 v49, v48
